# v21 + per-tile index calc in the three K=1024 tile loops specialised: group size is always 8 (nM=384), so the 30-instruction runtime division (incl. v_rcp/v_readfirstlane chain) on the leading half's
# baseline (speedup 1.0000x reference)
;     __device__ __forceinline__ bool next(int i, Unit& u) const {
;         const long L = (long)i * G + c; if (L >= (long)nM * nN) return false;
;         tile_of((int)L, nM, nN, u.pm, u.pn); u.sub = 0;
;         u.A = A + (size_t)u.pm * BM * lda * 2; u.B = B + (size_t)u.pn * BM * ldb * 2; return true;
;     }
.LBB0_238:
	s_add_i32 s41, s41, 1
	s_mul_i32 s0, s41, s44
	s_mul_hi_u32 s1, s41, s45
	s_add_i32 s1, s1, s0
	s_mul_i32 s0, s41, s45
	s_add_u32 s26, s0, s2
	s_addc_u32 s27, s1, s33
	v_cmp_gt_i64_e32 vcc, s[26:27], v[212:213]
	v_cmp_lt_i64_e64 s[0:1], s[26:27], v[210:211]
	s_cbranch_vccnz .LBB0_240
	s_ashr_i32 s12, s26, 31
	s_lshr_b32 s12, s12, 29
	s_add_i32 s12, s26, s12
	s_ashr_i32 s13, s12, 3
	s_and_b32 s12, s12, -8
	s_sub_i32 s12, s26, s12
	s_cmp_lt_i32 s12, 0
	s_cselect_b32 s14, s36, 0x420
	s_mul_i32 s12, s12, s14
	s_add_i32 s12, s12, s13
	s_mul_hi_i32 s13, s12, 0x2e8ba2e9
	s_lshr_b32 s14, s13, 31
	s_ashr_i32 s13, s13, 5
	s_add_i32 s13, s13, s14
	s_lshl_b32 s14, s13, 3
	s_mulk_i32 s13, 0xb0
	s_sub_i32 s13, s12, s13
	s_ashr_i32 s12, s13, 3
	s_and_b32 s13, s13, 7
	s_add_i32 s14, s14, s13
	s_ashr_i32 s15, s14, 31
	s_lshl_b64 s[16:17], s[14:15], 19
	s_add_u32 s16, s60, s16
	s_addc_u32 s17, s61, s17
	s_ashr_i32 s13, s12, 31
	s_lshl_b64 s[18:19], s[12:13], 19
	s_add_u32 s18, s54, s18
	s_addc_u32 s19, s55, s19

;     __device__ __forceinline__ bool next(int i, Unit& u) const {
;         const long L = (long)i * G + c; if (L >= (long)nM * nN) return false;
;         tile_of((int)L, nM, nN, u.pm, u.pn); u.sub = 0;
;         u.A = A + (size_t)u.pm * BM * lda * 2; u.B = B + (size_t)u.pn * BM * ldb * 2; return true;
;     }
.LBB0_422:
	s_add_i32 s77, s77, 1
	s_mul_i32 s0, s77, s45
	s_mul_hi_u32 s1, s77, s62
	s_add_i32 s1, s1, s0
	s_mul_i32 s0, s77, s62
	s_add_u32 s10, s0, s2
	s_addc_u32 s11, s1, s37
	v_cmp_gt_i64_e32 vcc, s[10:11], v[218:219]
	v_cmp_lt_i64_e64 s[0:1], s[10:11], v[216:217]
	s_cbranch_vccnz .LBB0_424
	s_ashr_i32 s5, s10, 31
	s_lshr_b32 s5, s5, 29
	s_add_i32 s5, s10, s5
	s_ashr_i32 s11, s5, 3
	s_and_b32 s5, s5, -8
	s_sub_i32 s5, s10, s5
	s_cmp_lt_i32 s5, 0
	s_cselect_b32 s10, s38, 0x390
	s_mul_i32 s5, s5, s10
	s_add_i32 s5, s5, s11
	s_mul_hi_i32 s10, s5, 0x6bca1af3
	s_lshr_b32 s11, s10, 31
	s_ashr_i32 s10, s10, 6
	s_add_i32 s10, s10, s11
	s_lshl_b32 s11, s10, 3
	s_mulk_i32 s10, 0x98
	s_sub_i32 s5, s5, s10
	s_ashr_i32 s50, s5, 3
	s_and_b32 s5, s5, 7
	s_add_i32 s68, s11, s5
	s_ashr_i32 s69, s68, 31
	s_lshl_b64 s[10:11], s[68:69], 19
	s_add_u32 s70, s60, s10
	s_addc_u32 s71, s61, s11
	s_ashr_i32 s51, s50, 31
	s_lshl_b64 s[10:11], s[50:51], 19
	s_add_u32 s72, s3, s10
	s_addc_u32 s73, s33, s11

;     __device__ __forceinline__ bool next(int i, Unit& u) const {
;         const long L = (long)i * G + c; if (L >= (long)nM * nN) return false;
;         tile_of((int)L, nM, nN, u.pm, u.pn); u.sub = 0;
;         u.A = A + (size_t)u.pm * BM * lda * 2; u.B = B + (size_t)u.pn * BM * ldb * 2; return true;
;     }
.LBB0_1050:
	s_add_i32 s43, s43, 1
	s_mul_i32 s0, s43, s48
	s_mul_hi_u32 s1, s43, s49
	s_add_i32 s1, s1, s0
	s_mul_i32 s0, s43, s49
	s_add_u32 s26, s0, s2
	s_addc_u32 s27, s1, s37
	v_cmp_gt_i64_e32 vcc, s[26:27], v[212:213]
	v_cmp_lt_i64_e64 s[0:1], s[26:27], v[210:211]
	s_cbranch_vccnz .LBB0_1052
	s_ashr_i32 s12, s26, 31
	s_lshr_b32 s12, s12, 29
	s_add_i32 s12, s26, s12
	s_ashr_i32 s13, s12, 3
	s_and_b32 s12, s12, -8
	s_sub_i32 s12, s26, s12
	s_cmp_lt_i32 s12, 0
	s_cselect_b32 s14, s38, 0x420
	s_mul_i32 s12, s12, s14
	s_add_i32 s12, s12, s13
	s_mul_hi_i32 s13, s12, 0x2e8ba2e9
	s_lshr_b32 s14, s13, 31
	s_ashr_i32 s13, s13, 5
	s_add_i32 s13, s13, s14
	s_lshl_b32 s14, s13, 3
	s_mulk_i32 s13, 0xb0
	s_sub_i32 s13, s12, s13
	s_ashr_i32 s12, s13, 3
	s_and_b32 s13, s13, 7
	s_add_i32 s14, s14, s13
	s_ashr_i32 s15, s14, 31
	s_lshl_b64 s[16:17], s[14:15], 19
	s_add_u32 s16, s60, s16
	s_addc_u32 s17, s61, s17
	s_ashr_i32 s13, s12, 31
	s_lshl_b64 s[18:19], s[12:13], 19
	s_add_u32 s18, s3, s18
	s_addc_u32 s19, s33, s19
